# P1 round 8 tiles handed to the workgroups whose regular tiles have the cheaper epilogue mix
# speedup vs baseline: 1.2504x; 1.0005x over previous
.LBB0_193:
	s_and_b64 vcc, exec, s[92:93]
	s_cbranch_vccz .LBB0_197
	s_lshr_b32 s25, s22, 5
	s_add_i32 s25, s25, s22
	s_and_b32 s25, s25, 1
	s_cmp_eq_u32 s25, 0
	s_cbranch_scc0 .LBB0_214
	s_lshr_b32 s25, s22, 3
	s_lshl_b32 s25, s25, 2
	s_bfe_u32 s26, s22, 0x20001
	s_or_b32 s25, s25, s26
	s_cmp_gt_i32 s25, 15
	s_cbranch_scc0 .LBB0_198
	s_cmp_lt_u32 s25, 48
	s_cbranch_scc0 .LBB0_214
	s_waitcnt lgkmcnt(0)
	v_readlane_b32 s10, v253, 42
	v_readlane_b32 s11, v253, 43
	s_load_dwordx2 s[10:11], s[10:11], 0x98
	s_add_i32 s0, s25, -16
	s_lshr_b32 s23, s0, 1
	s_and_b32 s24, s25, 1
	s_mov_b64 s[0:1], -1
	s_mov_b64 s[8:9], 0
	s_branch .LBB0_200

.LBB0_198:
	s_mov_b32 s23, 0
	s_mov_b64 s[8:9], -1
	s_waitcnt lgkmcnt(0)
	s_mov_b64 s[10:11], s[6:7]
	s_mov_b32 s24, s25
	s_mov_b64 s[0:1], -1
	s_branch .LBB0_200
